# NA latent item prologue de-serialised: bias-table load no longer drained before the Q/K/V loads; its scale + LDS write happen behind the wait those loads already have (both wave-parity copies)
# speedup vs baseline: 1.0017x; 1.0017x over previous
.LBB0_1091:
	s_bfe_u32 s70, s71, 0x40004
	s_mov_b64 s[0:1], exec
	v_readlane_b32 s72, v238, 23
	v_readlane_b32 s73, v238, 24
	s_and_b64 s[72:73], s[0:1], s[72:73]
	s_mov_b64 exec, s[72:73]
	s_cbranch_execz .LBB0_1093
	v_readlane_b32 s72, v238, 10
	v_readlane_b32 s73, v238, 11
	s_load_dwordx2 s[72:73], s[72:73], 0x98
	s_mul_i32 s74, s70, 0x1d1
	v_add_lshl_u32 v0, s74, v192, 2
	s_waitcnt lgkmcnt(0)
	s_nop 0
	global_load_dword v239, v0, s[72:73]
.LBB0_1093:
	s_or_b64 exec, exec, s[0:1]
	s_lshl_b32 s1, s71, 2
	s_and_b32 s86, s1, 60
	v_sub_u32_e64 v0, s86, 4 clamp
	s_ashr_i32 s0, s71, 8
	v_readfirstlane_b32 s87, v0
	v_sub_u32_e64 v0, s86, 1 clamp
	v_readlane_b32 s78, v238, 14
	v_readfirstlane_b32 s1, v0
	s_min_u32 s1, s1, 56
	s_sub_i32 s84, s1, s87
	s_add_i32 s80, s84, 7
	s_and_b32 s91, s80, -2
	s_ashr_i32 s1, s0, 31
	s_add_i32 s85, s91, 6
	s_lshl_b64 s[72:73], s[0:1], 12
	s_add_u32 s72, s72, 0x2000
	s_addc_u32 s73, s73, 0
	s_lshl_b32 s71, s86, 6
	s_or_b32 s74, s72, s71
	s_mov_b32 s75, s73
	s_lshl_b64 s[74:75], s[74:75], 11
	v_readlane_b32 s79, v238, 15
	s_add_u32 s71, s78, s74
	s_addc_u32 s77, s79, s75
	s_lshl_b32 s78, s70, 7
	s_add_u32 s70, s71, s78
	s_addc_u32 s71, s77, 0
	s_lshl_b64 s[0:1], s[0:1], 19
	v_readlane_b32 s77, v238, 17
	s_add_u32 s77, s77, s0
	v_readlane_b32 s79, v238, 18
	s_addc_u32 s79, s79, s1
	s_add_u32 s82, s77, s78
	s_addc_u32 s83, s79, 0
	v_readlane_b32 s77, v238, 19
	s_add_u32 s0, s77, s0
	v_readlane_b32 s77, v238, 20
	s_addc_u32 s1, s77, s1
	s_add_u32 s92, s0, s78
	s_addc_u32 s93, s1, 0
	s_lshl_b64 s[0:1], s[72:73], 11
	s_add_u32 s72, s81, s0
	s_addc_u32 s73, s88, s1
	s_add_u32 s96, s72, s78
	s_addc_u32 s97, s73, 0
	s_add_u32 s0, s89, s0
	s_addc_u32 s1, s94, s1
	s_add_u32 s0, s0, s78
	s_addc_u32 s1, s1, 0
	s_add_u32 s72, s95, s74
	v_readlane_b32 s73, v238, 16
	v_lshl_add_u64 v[0:1], s[70:71], 0, v[156:157]
	v_add_u32_e32 v197, s86, v181
	s_addc_u32 s73, s73, s75
	v_lshl_add_u64 v[160:161], v[0:1], 0, v[152:153]
	v_sub_u32_e64 v0, v197, 4 clamp
	s_add_u32 s94, s72, s78
	v_min_u32_e32 v175, 56, v0
	v_lshl_add_u64 v[0:1], s[82:83], 0, v[158:159]
	s_addc_u32 s95, s73, 0
	v_readfirstlane_b32 s72, v192
	v_lshl_add_u64 v[162:163], v[0:1], 0, v[148:149]
	v_lshl_add_u64 v[0:1], s[92:93], 0, v[158:159]
	s_bitcmp0_b32 s72, 6
	v_lshl_add_u64 v[164:165], v[0:1], 0, v[148:149]
	s_mov_b64 s[70:71], -1
	s_waitcnt lgkmcnt(0)
	s_barrier
	s_cbranch_scc1 .LBB0_1320
	global_load_dwordx4 v[132:135], v[164:165], off
	global_load_dwordx4 v[128:131], v[162:163], off
	global_load_dwordx4 v[124:127], v[160:161], off
	global_load_dwordx4 v[120:123], v[160:161], off offset:32
	global_load_dwordx4 v[116:119], v[160:161], off offset:64
	global_load_dwordx4 v[112:115], v[160:161], off offset:96
	s_waitcnt vmcnt(0)
	v_readlane_b32 s100, v238, 23
	v_readlane_b32 s101, v238, 24
	s_nop 3
	s_and_saveexec_b64 s[98:99], s[100:101]
	v_mul_f32_e32 v239, 0x3fb8aa3b, v239
	ds_write_b32 v186, v239 offset:32768
	s_mov_b64 exec, s[98:99]
	v_mov_b32_e32 v155, v149
	v_lshl_add_u64 v[66:67], s[82:83], 0, v[154:155]
	s_mov_b32 s70, 0x20000
	v_lshl_add_u64 v[64:65], s[92:93], 0, v[154:155]
	v_readfirstlane_b32 s77, v175
	s_cmp_lt_i32 s91, -3
	s_waitcnt vmcnt(5)
	ds_write_b128 v189, v[132:135]
	s_waitcnt vmcnt(4)
	ds_write_b128 v190, v[128:131] offset:16384
	s_waitcnt lgkmcnt(0)
	s_barrier
	ds_read_b128 v[0:3], v191 offset:16384
	ds_read_b128 v[4:7], v191 offset:20480
	s_waitcnt vmcnt(3) lgkmcnt(1)
	v_mfma_f32_32x32x16_bf16 v[16:31], v[0:3], v[124:127], 0
	ds_read_b128 v[0:3], v193 offset:16384
	ds_read_b128 v[32:35], v193 offset:20480
	s_waitcnt vmcnt(2) lgkmcnt(1)
	v_mfma_f32_32x32x16_bf16 v[16:31], v[0:3], v[120:123], v[16:31]
	v_mfma_f32_32x32x16_bf16 v[0:15], v[4:7], v[124:127], 0
	s_waitcnt lgkmcnt(0)
	v_mfma_f32_32x32x16_bf16 v[0:15], v[32:35], v[120:123], v[0:15]
	ds_read_b128 v[32:35], v194 offset:16384
	ds_read_b128 v[36:39], v194 offset:20480
	s_waitcnt vmcnt(1) lgkmcnt(1)
	v_mfma_f32_32x32x16_bf16 v[16:31], v[32:35], v[116:119], v[16:31]
	s_waitcnt lgkmcnt(0)
	v_mfma_f32_32x32x16_bf16 v[0:15], v[36:39], v[116:119], v[0:15]
	ds_read_b128 v[32:35], v195 offset:16384
	ds_read_b128 v[36:39], v195 offset:20480
	s_waitcnt vmcnt(0) lgkmcnt(1)
	v_mfma_f32_32x32x16_bf16 v[16:31], v[32:35], v[112:115], v[16:31]
	v_lshl_add_u64 v[32:33], v[66:67], 0, v[148:149]
	v_add_co_u32_e32 v32, vcc, s70, v32
	v_lshl_add_u64 v[34:35], v[64:65], 0, v[148:149]
	s_nop 0
	v_addc_co_u32_e32 v33, vcc, 0, v33, vcc
	s_waitcnt lgkmcnt(0)
	v_mfma_f32_32x32x16_bf16 v[0:15], v[36:39], v[112:115], v[0:15]
	v_add_co_u32_e32 v36, vcc, 0x20000, v34
	s_nop 3
	v_max_f32_e32 v34, v17, v17
	v_addc_co_u32_e32 v37, vcc, 0, v35, vcc
	v_max_f32_e32 v35, v16, v16
	v_max_f32_e32 v34, v35, v34
	v_max3_f32 v34, v34, v18, v19
	v_max3_f32 v34, v34, v20, v21
	v_max3_f32 v34, v34, v22, v23
	v_max3_f32 v34, v34, v24, v25
	v_max3_f32 v34, v34, v26, v27
	v_max3_f32 v34, v34, v28, v29
	v_max3_f32 v34, v34, v30, v31
	v_max3_f32 v34, v34, v0, v1
	v_max3_f32 v34, v34, v2, v3
	v_max3_f32 v34, v34, v4, v5
	v_max3_f32 v34, v34, v6, v7
	v_max3_f32 v34, v34, v8, v9
	v_max3_f32 v34, v34, v10, v11
	v_max3_f32 v34, v34, v12, v13
	v_max3_f32 v34, v34, v14, v15
	v_mov_b32_e32 v35, v34
	s_nop 1
	v_permlane32_swap_b32_e32 v34, v35
	v_max_f32_e32 v35, v35, v35
	v_max_f32_e32 v34, v34, v34
	v_max_f32_e32 v40, v34, v35
	v_add_f32_e32 v34, 0x7149f2ca, v40
	v_cmp_ge_f32_e64 s[70:71], s2, v34
	global_load_dwordx4 v[32:35], v[32:33], off
	s_nop 0
	global_load_dwordx4 v[36:39], v[36:37], off
	s_cbranch_scc1 .LBB0_1096
	v_lshl_add_u64 v[44:45], v[66:67], 0, v[148:149]
	v_add_co_u32_e32 v44, vcc, 0x40000, v44
	v_lshl_add_u64 v[42:43], v[64:65], 0, v[148:149]
	s_nop 0
	v_addc_co_u32_e32 v45, vcc, 0, v45, vcc
	v_add_co_u32_e32 v42, vcc, 0x40000, v42
	s_nop 1
	v_addc_co_u32_e32 v43, vcc, 0, v43, vcc
	global_load_dwordx4 v[128:131], v[44:45], off
	global_load_dwordx4 v[132:135], v[42:43], off

.LBB0_1320:
	s_and_b64 vcc, exec, s[70:71]
	s_cbranch_vccz .LBB0_1085
	global_load_dwordx4 v[118:121], v[164:165], off
	global_load_dwordx4 v[114:117], v[162:163], off
	global_load_dwordx4 v[110:113], v[160:161], off
	global_load_dwordx4 v[106:109], v[160:161], off offset:32
	global_load_dwordx4 v[102:105], v[160:161], off offset:64
	global_load_dwordx4 v[98:101], v[160:161], off offset:96
	s_waitcnt vmcnt(0)
	v_readlane_b32 s100, v238, 23
	v_readlane_b32 s101, v238, 24
	s_nop 3
	s_and_saveexec_b64 s[98:99], s[100:101]
	v_mul_f32_e32 v239, 0x3fb8aa3b, v239
	ds_write_b32 v186, v239 offset:32768
	s_mov_b64 exec, s[98:99]
	v_mov_b32_e32 v155, v149
	s_mov_b32 s70, 0x20000
	v_readfirstlane_b32 s77, v175
	s_cmp_lt_i32 s91, -3
	s_waitcnt vmcnt(5)
	ds_write_b128 v189, v[118:121]
	s_waitcnt vmcnt(4)
	ds_write_b128 v190, v[114:117] offset:16384
	s_waitcnt lgkmcnt(0)
	s_barrier
	ds_read_b128 v[0:3], v191 offset:16384
	ds_read_b128 v[4:7], v191 offset:20480
	s_waitcnt vmcnt(3) lgkmcnt(1)
	v_mfma_f32_32x32x16_bf16 v[16:31], v[0:3], v[110:113], 0
	ds_read_b128 v[32:35], v193 offset:16384
	ds_read_b128 v[36:39], v193 offset:20480
	ds_read_b128 v[40:43], v195 offset:20480
	s_waitcnt lgkmcnt(3)
	v_mfma_f32_32x32x16_bf16 v[0:15], v[4:7], v[110:113], 0
	s_waitcnt vmcnt(2) lgkmcnt(2)
	v_mfma_f32_32x32x16_bf16 v[16:31], v[32:35], v[106:109], v[16:31]
	ds_read_b128 v[32:35], v194 offset:16384
	s_waitcnt lgkmcnt(2)
	v_mfma_f32_32x32x16_bf16 v[0:15], v[36:39], v[106:109], v[0:15]
	ds_read_b128 v[36:39], v194 offset:20480
	s_waitcnt vmcnt(1) lgkmcnt(1)
	v_mfma_f32_32x32x16_bf16 v[16:31], v[32:35], v[102:105], v[16:31]
	v_lshl_add_u64 v[32:33], s[82:83], 0, v[154:155]
	v_lshl_add_u64 v[34:35], s[92:93], 0, v[154:155]
	v_lshl_add_u64 v[66:67], v[32:33], 0, v[148:149]
	v_lshl_add_u64 v[64:65], v[34:35], 0, v[148:149]
	ds_read_b128 v[32:35], v195 offset:16384
	v_add_co_u32_e32 v44, vcc, s70, v66
	s_waitcnt lgkmcnt(1)
	v_mfma_f32_32x32x16_bf16 v[0:15], v[36:39], v[102:105], v[0:15]
	v_addc_co_u32_e32 v45, vcc, 0, v67, vcc
	v_add_co_u32_e32 v36, vcc, 0x20000, v64
	s_nop 1
	v_addc_co_u32_e32 v37, vcc, 0, v65, vcc
	s_waitcnt vmcnt(0) lgkmcnt(0)
	v_mfma_f32_32x32x16_bf16 v[16:31], v[32:35], v[98:101], v[16:31]
	global_load_dwordx4 v[32:35], v[44:45], off
	s_nop 0
	global_load_dwordx4 v[36:39], v[36:37], off
	v_mfma_f32_32x32x16_bf16 v[0:15], v[40:43], v[98:101], v[0:15]
	s_nop 7
	v_max_f32_e32 v40, v17, v17
	v_max_f32_e32 v41, v16, v16
	v_max_f32_e32 v40, v41, v40
	v_max3_f32 v40, v40, v18, v19
	v_max3_f32 v40, v40, v20, v21
	v_max3_f32 v40, v40, v22, v23
	v_max3_f32 v40, v40, v24, v25
	v_max3_f32 v40, v40, v26, v27
	v_max3_f32 v40, v40, v28, v29
	v_max3_f32 v40, v40, v30, v31
	v_max3_f32 v40, v40, v0, v1
	v_max3_f32 v40, v40, v2, v3
	v_max3_f32 v40, v40, v4, v5
	v_max3_f32 v40, v40, v6, v7
	v_max3_f32 v40, v40, v8, v9
	v_max3_f32 v40, v40, v10, v11
	v_max3_f32 v40, v40, v12, v13
	v_max3_f32 v40, v40, v14, v15
	v_mov_b32_e32 v41, v40
	s_nop 1
	v_permlane32_swap_b32_e32 v40, v41
	v_max_f32_e32 v41, v41, v41
	v_max_f32_e32 v40, v40, v40
	v_max_f32_e32 v40, v40, v41
	v_add_f32_e32 v41, 0x7149f2ca, v40
	v_cmp_ge_f32_e64 s[70:71], s2, v41
	s_cbranch_scc1 .LBB0_1323
	v_add_co_u32_e32 v42, vcc, 0x40000, v66
	s_nop 1
	v_addc_co_u32_e32 v43, vcc, 0, v67, vcc
	v_add_co_u32_e32 v44, vcc, 0x40000, v64
	s_nop 1
	v_addc_co_u32_e32 v45, vcc, 0, v65, vcc
	global_load_dwordx4 v[114:117], v[42:43], off
	global_load_dwordx4 v[118:121], v[44:45], off

	.amdhsa_kernel _Z10fwd_kernel6Params
		.amdhsa_group_segment_fixed_size 0
		.amdhsa_private_segment_fixed_size 0
		.amdhsa_kernarg_size 440
		.amdhsa_user_sgpr_count 2
		.amdhsa_user_sgpr_dispatch_ptr 0
		.amdhsa_user_sgpr_queue_ptr 0
		.amdhsa_user_sgpr_kernarg_segment_ptr 1
		.amdhsa_user_sgpr_dispatch_id 0
		.amdhsa_user_sgpr_kernarg_preload_length 0
		.amdhsa_user_sgpr_kernarg_preload_offset 0
		.amdhsa_user_sgpr_private_segment_size 0
		.amdhsa_uses_dynamic_stack 0
		.amdhsa_enable_private_segment 0
		.amdhsa_system_sgpr_workgroup_id_x 1
		.amdhsa_system_sgpr_workgroup_id_y 0
		.amdhsa_system_sgpr_workgroup_id_z 0
		.amdhsa_system_sgpr_workgroup_info 0
		.amdhsa_system_vgpr_workitem_id 2
		.amdhsa_next_free_vgpr 256
		.amdhsa_next_free_sgpr 102
		.amdhsa_accum_offset 256
		.amdhsa_reserve_vcc 1
		.amdhsa_float_round_mode_32 0
		.amdhsa_float_round_mode_16_64 0
		.amdhsa_float_denorm_mode_32 3
		.amdhsa_float_denorm_mode_16_64 3
		.amdhsa_dx10_clamp 1
		.amdhsa_ieee_mode 1
		.amdhsa_fp16_overflow 0
		.amdhsa_tg_split 0
		.amdhsa_exception_fp_ieee_invalid_op 0
		.amdhsa_exception_fp_denorm_src 0
		.amdhsa_exception_fp_ieee_div_zero 0
		.amdhsa_exception_fp_ieee_overflow 0
		.amdhsa_exception_fp_ieee_underflow 0
		.amdhsa_exception_fp_ieee_inexact 0
		.amdhsa_exception_int_div_zero 0
	.end_amdhsa_kernel

amdhsa.kernels:
  - .agpr_count:     0
    .args:
      - .offset:         0
        .size:           184
        .value_kind:     by_value
      - .offset:         184
        .size:           4
        .value_kind:     hidden_block_count_x
      - .offset:         188
        .size:           4
        .value_kind:     hidden_block_count_y
      - .offset:         192
        .size:           4
        .value_kind:     hidden_block_count_z
      - .offset:         196
        .size:           2
        .value_kind:     hidden_group_size_x
      - .offset:         198
        .size:           2
        .value_kind:     hidden_group_size_y
      - .offset:         200
        .size:           2
        .value_kind:     hidden_group_size_z
      - .offset:         202
        .size:           2
        .value_kind:     hidden_remainder_x
      - .offset:         204
        .size:           2
        .value_kind:     hidden_remainder_y
      - .offset:         206
        .size:           2
        .value_kind:     hidden_remainder_z
      - .offset:         224
        .size:           8
        .value_kind:     hidden_global_offset_x
      - .offset:         232
        .size:           8
        .value_kind:     hidden_global_offset_y
      - .offset:         240
        .size:           8
        .value_kind:     hidden_global_offset_z
      - .offset:         248
        .size:           2
        .value_kind:     hidden_grid_dims
      - .offset:         272
        .size:           8
        .value_kind:     hidden_multigrid_sync_arg
      - .offset:         304
        .size:           4
        .value_kind:     hidden_dynamic_lds_size
    .group_segment_fixed_size: 0
    .kernarg_segment_align: 8
    .kernarg_segment_size: 440
    .language:       OpenCL C
    .language_version:
      - 2
      - 0
    .max_flat_workgroup_size: 512
    .name:           _Z10fwd_kernel6Params
    .private_segment_fixed_size: 0
    .sgpr_count:     108
    .sgpr_spill_count: 37
    .symbol:         _Z10fwd_kernel6Params.kd
    .uniform_work_group_size: 1
    .uses_dynamic_stack: false
    .vgpr_count:     256
    .vgpr_spill_count: 0
    .wavefront_size: 64
